# GEMM accumulator zeroing via v_mov_b64 pairs; P0 GEMV last batch peeled and next-batch weight lines touched early (L2 prefetch) with counted waits bumped
# speedup vs baseline: 1.0028x; 1.0028x over previous
.LBB0_35:
	s_ashr_i32 s47, s46, 31
	s_lshl_b64 s[10:11], s[46:47], 20
	s_add_u32 s52, s12, s10
	s_addc_u32 s53, s13, s11
	s_and_b64 s[10:11], s[40:41], exec
	s_cselect_b32 s47, s53, s7
	s_cselect_b32 s63, s52, s6
	s_ashr_i32 s45, s44, 31
	s_lshl_b64 s[10:11], s[44:45], 20
	s_add_u32 s54, s5, s10
	s_addc_u32 s55, s14, s11
	s_and_b64 s[10:11], s[40:41], exec
	s_cselect_b32 s45, s55, s9
	s_cselect_b32 s64, s54, s8
	s_add_u32 s6, s6, 0x80080
	s_addc_u32 s7, s7, 0
	s_add_u32 s65, s8, 0x100
	v_mov_b32_e32 v2, 0
	s_addc_u32 s66, s9, 0
	s_mov_b32 s67, -2
	v_mov_b32_e32 v3, v2
	v_mov_b64_e32 v[4:5], v[2:3]
	v_mov_b64_e32 v[6:7], v[2:3]
	v_mov_b64_e32 v[8:9], v[2:3]
	v_mov_b64_e32 v[10:11], v[2:3]
	v_mov_b64_e32 v[12:13], v[2:3]
	v_mov_b64_e32 v[14:15], v[2:3]
	v_mov_b64_e32 v[16:17], v[2:3]
	v_mov_b64_e32 v[18:19], v[2:3]
	v_mov_b64_e32 v[20:21], v[2:3]
	v_mov_b64_e32 v[22:23], v[2:3]
	v_mov_b64_e32 v[24:25], v[2:3]
	v_mov_b64_e32 v[26:27], v[2:3]
	v_mov_b64_e32 v[28:29], v[2:3]
	v_mov_b64_e32 v[30:31], v[2:3]
	v_mov_b64_e32 v[32:33], v[2:3]
	v_mov_b64_e32 v[34:35], v[2:3]
	v_mov_b64_e32 v[36:37], v[2:3]
	v_mov_b64_e32 v[38:39], v[2:3]
	v_mov_b64_e32 v[40:41], v[2:3]
	v_mov_b64_e32 v[42:43], v[2:3]
	v_mov_b64_e32 v[44:45], v[2:3]
	v_mov_b64_e32 v[46:47], v[2:3]
	v_mov_b64_e32 v[48:49], v[2:3]
	v_mov_b64_e32 v[50:51], v[2:3]
	v_mov_b64_e32 v[52:53], v[2:3]
	v_mov_b64_e32 v[54:55], v[2:3]
	v_mov_b64_e32 v[56:57], v[2:3]
	v_mov_b64_e32 v[58:59], v[2:3]
	v_mov_b64_e32 v[60:61], v[2:3]
	v_mov_b64_e32 v[62:63], v[2:3]
	v_mov_b64_e32 v[64:65], v[2:3]
	v_mov_b64_e32 v[66:67], v[2:3]
	v_mov_b64_e32 v[68:69], v[2:3]
	v_mov_b64_e32 v[70:71], v[2:3]
	v_mov_b64_e32 v[72:73], v[2:3]
	v_mov_b64_e32 v[74:75], v[2:3]
	v_mov_b64_e32 v[76:77], v[2:3]
	v_mov_b64_e32 v[78:79], v[2:3]
	v_mov_b64_e32 v[80:81], v[2:3]
	v_mov_b64_e32 v[82:83], v[2:3]
	v_mov_b64_e32 v[84:85], v[2:3]
	v_mov_b64_e32 v[86:87], v[2:3]
	v_mov_b64_e32 v[88:89], v[2:3]
	v_mov_b64_e32 v[90:91], v[2:3]
	v_mov_b64_e32 v[92:93], v[2:3]
	v_mov_b64_e32 v[94:95], v[2:3]
	v_mov_b64_e32 v[96:97], v[2:3]
	v_mov_b64_e32 v[98:99], v[2:3]
	v_mov_b64_e32 v[100:101], v[2:3]
	v_mov_b64_e32 v[102:103], v[2:3]
	v_mov_b64_e32 v[104:105], v[2:3]
	v_mov_b64_e32 v[106:107], v[2:3]
	v_mov_b64_e32 v[108:109], v[2:3]
	v_mov_b64_e32 v[110:111], v[2:3]
	v_mov_b64_e32 v[112:113], v[2:3]
	v_mov_b64_e32 v[114:115], v[2:3]
	v_mov_b64_e32 v[116:117], v[2:3]
	v_mov_b64_e32 v[118:119], v[2:3]
	v_mov_b64_e32 v[120:121], v[2:3]
	v_mov_b64_e32 v[122:123], v[2:3]
	v_mov_b64_e32 v[124:125], v[2:3]
	v_mov_b64_e32 v[126:127], v[2:3]
	v_mov_b64_e32 v[128:129], v[2:3]

.LBB0_349:
	s_add_u32 s8, s8, 0x80
	s_addc_u32 s9, s9, 0
	s_add_u32 s12, s10, 0x100
	v_mov_b32_e32 v2, 0
	s_addc_u32 s13, s11, 0
	s_mov_b32 s10, 0
	v_mov_b32_e32 v3, v2
	v_mov_b64_e32 v[4:5], v[2:3]
	v_mov_b64_e32 v[6:7], v[2:3]
	v_mov_b64_e32 v[8:9], v[2:3]
	v_mov_b64_e32 v[10:11], v[2:3]
	v_mov_b64_e32 v[12:13], v[2:3]
	v_mov_b64_e32 v[14:15], v[2:3]
	v_mov_b64_e32 v[16:17], v[2:3]
	v_mov_b64_e32 v[18:19], v[2:3]
	v_mov_b64_e32 v[20:21], v[2:3]
	v_mov_b64_e32 v[22:23], v[2:3]
	v_mov_b64_e32 v[24:25], v[2:3]
	v_mov_b64_e32 v[26:27], v[2:3]
	v_mov_b64_e32 v[28:29], v[2:3]
	v_mov_b64_e32 v[30:31], v[2:3]
	v_mov_b64_e32 v[32:33], v[2:3]
	v_mov_b64_e32 v[34:35], v[2:3]
	v_mov_b64_e32 v[36:37], v[2:3]
	v_mov_b64_e32 v[38:39], v[2:3]
	v_mov_b64_e32 v[40:41], v[2:3]
	v_mov_b64_e32 v[42:43], v[2:3]
	v_mov_b64_e32 v[44:45], v[2:3]
	v_mov_b64_e32 v[46:47], v[2:3]
	v_mov_b64_e32 v[48:49], v[2:3]
	v_mov_b64_e32 v[50:51], v[2:3]
	v_mov_b64_e32 v[52:53], v[2:3]
	v_mov_b64_e32 v[54:55], v[2:3]
	v_mov_b64_e32 v[56:57], v[2:3]
	v_mov_b64_e32 v[58:59], v[2:3]
	v_mov_b64_e32 v[60:61], v[2:3]
	v_mov_b64_e32 v[62:63], v[2:3]
	v_mov_b64_e32 v[64:65], v[2:3]
	v_mov_b64_e32 v[66:67], v[2:3]
	v_mov_b64_e32 v[68:69], v[2:3]
	v_mov_b64_e32 v[70:71], v[2:3]
	v_mov_b64_e32 v[72:73], v[2:3]
	v_mov_b64_e32 v[74:75], v[2:3]
	v_mov_b64_e32 v[76:77], v[2:3]
	v_mov_b64_e32 v[78:79], v[2:3]
	v_mov_b64_e32 v[80:81], v[2:3]
	v_mov_b64_e32 v[82:83], v[2:3]
	v_mov_b64_e32 v[84:85], v[2:3]
	v_mov_b64_e32 v[86:87], v[2:3]
	v_mov_b64_e32 v[88:89], v[2:3]
	v_mov_b64_e32 v[90:91], v[2:3]
	v_mov_b64_e32 v[92:93], v[2:3]
	v_mov_b64_e32 v[94:95], v[2:3]
	v_mov_b64_e32 v[96:97], v[2:3]
	v_mov_b64_e32 v[98:99], v[2:3]
	v_mov_b64_e32 v[100:101], v[2:3]
	v_mov_b64_e32 v[102:103], v[2:3]
	v_mov_b64_e32 v[104:105], v[2:3]
	v_mov_b64_e32 v[106:107], v[2:3]
	v_mov_b64_e32 v[108:109], v[2:3]
	v_mov_b64_e32 v[110:111], v[2:3]
	v_mov_b64_e32 v[112:113], v[2:3]
	v_mov_b64_e32 v[114:115], v[2:3]
	v_mov_b64_e32 v[116:117], v[2:3]
	v_mov_b64_e32 v[118:119], v[2:3]
	v_mov_b64_e32 v[120:121], v[2:3]
	v_mov_b64_e32 v[122:123], v[2:3]
	v_mov_b64_e32 v[124:125], v[2:3]
	v_mov_b64_e32 v[126:127], v[2:3]
	v_mov_b64_e32 v[128:129], v[2:3]

.LBB0_417:
	s_mov_b32 s5, 0xfeb00000
	v_add_co_u32_e64 v2, s[42:43], s5, v20
	s_mov_b32 s5, 0xfee00000
	s_nop 0
	v_addc_co_u32_e64 v3, s[42:43], -1, v21, s[42:43]
	v_add_co_u32_e64 v4, s[42:43], s5, v20
	s_mov_b32 s5, 0xff100000
	s_nop 0
	v_addc_co_u32_e64 v5, s[42:43], -1, v21, s[42:43]
	v_add_co_u32_e64 v6, s[42:43], s5, v20
	s_mov_b32 s5, 0xff400000
	s_nop 0
	v_addc_co_u32_e64 v7, s[42:43], -1, v21, s[42:43]
	v_add_co_u32_e64 v8, s[42:43], s5, v20
	s_mov_b32 s5, 0xff700000
	s_nop 0
	v_addc_co_u32_e64 v9, s[42:43], -1, v21, s[42:43]
	v_add_co_u32_e64 v10, s[42:43], s5, v20
	s_mov_b32 s5, 0xffa00000
	s_nop 0
	v_addc_co_u32_e64 v11, s[42:43], -1, v21, s[42:43]
	v_add_co_u32_e64 v12, s[42:43], s5, v20
	s_mov_b32 s5, 0xffd00000
	s_nop 0
	v_addc_co_u32_e64 v13, s[42:43], -1, v21, s[42:43]
	v_add_co_u32_e64 v46, s[42:43], s5, v20
	v_add_u32_e32 v65, s4, v17
	s_nop 0
	v_addc_co_u32_e64 v47, s[42:43], -1, v21, s[42:43]
	global_load_dwordx4 v[60:63], v[2:3], off
	global_load_dwordx4 v[78:81], v[4:5], off
	global_load_dwordx4 v[82:85], v[6:7], off
	global_load_dwordx4 v[86:89], v[8:9], off
	global_load_dwordx4 v[90:93], v[10:11], off
	s_nop 0
	global_load_dwordx4 v[10:13], v[12:13], off
	s_nop 0
	global_load_dwordx4 v[6:9], v[46:47], off
	global_load_dwordx4 v[2:5], v[20:21], off
	v_add_u32_e32 v0, 0x10000, v65
	v_add_u32_e32 v22, 0x10100, v65
	v_add_u32_e32 v47, 0x10200, v65
	v_add_u32_e32 v48, 0x10300, v65
	v_add_u32_e32 v49, 0x10400, v65
	v_add_u32_e32 v50, 0x10500, v65
	v_add_u32_e32 v51, 0x10600, v65
	v_add_u32_e32 v71, 0x10700, v65
	ds_read_b32 v46, v0
	ds_read_b32 v64, v22
	ds_read_b32 v70, v47
	ds_read_b32 v74, v48
	ds_read_b32 v94, v49
	ds_read_b32 v52, v50
	ds_read_b32 v22, v51
	ds_read_b32 v0, v71
	ds_read2st64_b32 v[100:101], v65 offset1:1
	ds_read2st64_b32 v[102:103], v65 offset0:2 offset1:3
	ds_read2st64_b32 v[104:105], v65 offset0:4 offset1:5
	ds_read2st64_b32 v[50:51], v65 offset0:6 offset1:7
	ds_read2st64_b32 v[106:107], v65 offset0:32 offset1:33
	ds_read2st64_b32 v[108:109], v65 offset0:34 offset1:35
	ds_read2st64_b32 v[110:111], v65 offset0:36 offset1:37
	ds_read2st64_b32 v[48:49], v65 offset0:38 offset1:39
	s_addk_i32 s4, 0x800
	s_mov_b64 s[8:9], 0x1800000
	v_lshl_add_u64 v[20:21], v[20:21], 0, s[8:9]
	s_mov_b32 s5, 0xfeb00000
	v_add_co_u32_e64 v170, s[42:43], s5, v20
	s_nop 1
	v_addc_co_u32_e64 v171, s[42:43], -1, v21, s[42:43]
	global_load_dword v172, v[170:171], off
	s_mov_b32 s5, 0xfee00000
	v_add_co_u32_e64 v170, s[42:43], s5, v20
	s_nop 1
	v_addc_co_u32_e64 v171, s[42:43], -1, v21, s[42:43]
	global_load_dword v172, v[170:171], off
	s_mov_b32 s5, 0xff100000
	v_add_co_u32_e64 v170, s[42:43], s5, v20
	s_nop 1
	v_addc_co_u32_e64 v171, s[42:43], -1, v21, s[42:43]
	global_load_dword v172, v[170:171], off
	s_mov_b32 s5, 0xff400000
	v_add_co_u32_e64 v170, s[42:43], s5, v20
	s_nop 1
	v_addc_co_u32_e64 v171, s[42:43], -1, v21, s[42:43]
	global_load_dword v172, v[170:171], off
	s_mov_b32 s5, 0xff700000
	v_add_co_u32_e64 v170, s[42:43], s5, v20
	s_nop 1
	v_addc_co_u32_e64 v171, s[42:43], -1, v21, s[42:43]
	global_load_dword v172, v[170:171], off
	s_mov_b32 s5, 0xffa00000
	v_add_co_u32_e64 v170, s[42:43], s5, v20
	s_nop 1
	v_addc_co_u32_e64 v171, s[42:43], -1, v21, s[42:43]
	global_load_dword v172, v[170:171], off
	s_mov_b32 s5, 0xffd00000
	v_add_co_u32_e64 v170, s[42:43], s5, v20
	s_nop 1
	v_addc_co_u32_e64 v171, s[42:43], -1, v21, s[42:43]
	global_load_dword v172, v[170:171], off
	global_load_dword v172, v[20:21], off
	s_cmpk_eq_i32 s4, 0x1800
	s_waitcnt vmcnt(15) lgkmcnt(14)
	v_pk_fma_f32 v[96:97], v[60:61], v[46:47], v[26:27] op_sel_hi:[1,0,1]
	v_pk_fma_f32 v[98:99], v[62:63], v[46:47], v[24:25] op_sel_hi:[1,0,1]
	ds_read2st64_b32 v[112:113], v65 offset0:64 offset1:65
	ds_read2st64_b32 v[114:115], v65 offset0:66 offset1:67
	ds_read2st64_b32 v[116:117], v65 offset0:68 offset1:69
	ds_read2st64_b32 v[46:47], v65 offset0:70 offset1:71
	s_waitcnt lgkmcnt(11)
	v_pk_fma_f32 v[76:77], v[60:61], v[100:101], v[76:77] op_sel_hi:[1,0,1]
	s_waitcnt lgkmcnt(3)
	v_pk_fma_f32 v[118:119], v[62:63], v[112:113], v[44:45] op_sel_hi:[1,0,1]
	ds_read2st64_b32 v[120:121], v65 offset0:96 offset1:97
	ds_read2st64_b32 v[122:123], v65 offset0:98 offset1:99
	ds_read2st64_b32 v[124:125], v65 offset0:100 offset1:101
	ds_read2st64_b32 v[44:45], v65 offset0:102 offset1:103
	ds_read2st64_b32 v[128:129], v65 offset0:128 offset1:129
	ds_read2st64_b32 v[130:131], v65 offset0:130 offset1:131
	ds_read2st64_b32 v[132:133], v65 offset0:132 offset1:133
	ds_read2st64_b32 v[24:25], v65 offset0:134 offset1:135
	ds_read2st64_b32 v[134:135], v65 offset0:160 offset1:161
	ds_read2st64_b32 v[136:137], v65 offset0:162 offset1:163
	ds_read2st64_b32 v[138:139], v65 offset0:164 offset1:165
	ds_read2st64_b32 v[26:27], v65 offset0:166 offset1:167
	s_waitcnt lgkmcnt(11)
	v_pk_fma_f32 v[126:127], v[62:63], v[120:121], v[54:55] op_sel_hi:[1,0,1]
	s_waitcnt lgkmcnt(3)
	v_pk_fma_f32 v[140:141], v[62:63], v[134:135], v[28:29] op_sel_hi:[1,0,1]
	ds_read2st64_b32 v[142:143], v65 offset0:192 offset1:193
	ds_read2st64_b32 v[144:145], v65 offset0:194 offset1:195
	ds_read2st64_b32 v[146:147], v65 offset0:196 offset1:197
	ds_read2st64_b32 v[28:29], v65 offset0:198 offset1:199
	v_pk_fma_f32 v[72:73], v[62:63], v[100:101], v[72:73] op_sel_hi:[1,0,1]
	s_waitcnt lgkmcnt(3)
	v_pk_fma_f32 v[148:149], v[62:63], v[142:143], v[30:31] op_sel_hi:[1,0,1]
	ds_read2st64_b32 v[150:151], v65 offset0:224 offset1:225
	ds_read2st64_b32 v[152:153], v65 offset0:226 offset1:227
	ds_read2st64_b32 v[54:55], v65 offset0:228 offset1:229
	ds_read2st64_b32 v[30:31], v65 offset0:230 offset1:231
	v_pk_fma_f32 v[68:69], v[60:61], v[106:107], v[68:69] op_sel_hi:[1,0,1]
	v_pk_fma_f32 v[58:59], v[60:61], v[112:113], v[58:59] op_sel_hi:[1,0,1]
	v_pk_fma_f32 v[56:57], v[60:61], v[120:121], v[56:57] op_sel_hi:[1,0,1]
	v_pk_fma_f32 v[42:43], v[60:61], v[128:129], v[42:43] op_sel_hi:[1,0,1]
	v_pk_fma_f32 v[38:39], v[60:61], v[134:135], v[38:39] op_sel_hi:[1,0,1]
	v_pk_fma_f32 v[36:37], v[60:61], v[142:143], v[36:37] op_sel_hi:[1,0,1]
	s_waitcnt lgkmcnt(3)
	v_pk_fma_f32 v[34:35], v[60:61], v[150:151], v[34:35] op_sel_hi:[1,0,1]
	v_mov_b32_e32 v60, v101
	v_pk_fma_f32 v[66:67], v[62:63], v[106:107], v[66:67] op_sel_hi:[1,0,1]
	v_pk_fma_f32 v[40:41], v[62:63], v[128:129], v[40:41] op_sel_hi:[1,0,1]
	v_pk_fma_f32 v[32:33], v[62:63], v[150:151], v[32:33] op_sel_hi:[1,0,1]
	s_waitcnt vmcnt(14)
	v_pk_fma_f32 v[62:63], v[78:79], v[60:61], v[76:77] op_sel_hi:[1,0,1]
	v_pk_fma_f32 v[60:61], v[80:81], v[60:61], v[72:73] op_sel_hi:[1,0,1]
	v_mov_b32_e32 v72, v107
	v_mov_b32_e32 v100, v129
	v_pk_fma_f32 v[68:69], v[78:79], v[72:73], v[68:69] op_sel_hi:[1,0,1]
	v_pk_fma_f32 v[66:67], v[80:81], v[72:73], v[66:67] op_sel_hi:[1,0,1]
	v_mov_b32_e32 v72, v113
	v_mov_b32_e32 v76, v121
	v_pk_fma_f32 v[42:43], v[78:79], v[100:101], v[42:43] op_sel_hi:[1,0,1]
	v_pk_fma_f32 v[40:41], v[80:81], v[100:101], v[40:41] op_sel_hi:[1,0,1]
	v_mov_b32_e32 v100, v135
	v_mov_b32_e32 v106, v143
	v_mov_b32_e32 v112, v151
	v_pk_fma_f32 v[58:59], v[78:79], v[72:73], v[58:59] op_sel_hi:[1,0,1]
	v_pk_fma_f32 v[56:57], v[78:79], v[76:77], v[56:57] op_sel_hi:[1,0,1]
	v_pk_fma_f32 v[38:39], v[78:79], v[100:101], v[38:39] op_sel_hi:[1,0,1]
	v_pk_fma_f32 v[36:37], v[78:79], v[106:107], v[36:37] op_sel_hi:[1,0,1]
	v_pk_fma_f32 v[34:35], v[78:79], v[112:113], v[34:35] op_sel_hi:[1,0,1]
	v_pk_fma_f32 v[78:79], v[78:79], v[64:65], v[96:97] op_sel_hi:[1,0,1]
	s_waitcnt vmcnt(13)
	v_pk_fma_f32 v[62:63], v[82:83], v[102:103], v[62:63] op_sel_hi:[1,0,1]
	v_pk_fma_f32 v[78:79], v[82:83], v[70:71], v[78:79] op_sel_hi:[1,0,1]
	v_pk_fma_f32 v[60:61], v[84:85], v[102:103], v[60:61] op_sel_hi:[1,0,1]
	v_pk_fma_f32 v[68:69], v[82:83], v[108:109], v[68:69] op_sel_hi:[1,0,1]
	v_pk_fma_f32 v[58:59], v[82:83], v[114:115], v[58:59] op_sel_hi:[1,0,1]
	v_pk_fma_f32 v[56:57], v[82:83], v[122:123], v[56:57] op_sel_hi:[1,0,1]
	v_pk_fma_f32 v[42:43], v[82:83], v[130:131], v[42:43] op_sel_hi:[1,0,1]
	v_pk_fma_f32 v[38:39], v[82:83], v[136:137], v[38:39] op_sel_hi:[1,0,1]
	v_pk_fma_f32 v[36:37], v[82:83], v[144:145], v[36:37] op_sel_hi:[1,0,1]
	s_waitcnt lgkmcnt(2)
	v_pk_fma_f32 v[34:35], v[82:83], v[152:153], v[34:35] op_sel_hi:[1,0,1]
	v_mov_b32_e32 v82, v103
	v_pk_fma_f32 v[72:73], v[80:81], v[72:73], v[118:119] op_sel_hi:[1,0,1]
	v_pk_fma_f32 v[64:65], v[80:81], v[64:65], v[98:99] op_sel_hi:[1,0,1]
	v_pk_fma_f32 v[66:67], v[84:85], v[108:109], v[66:67] op_sel_hi:[1,0,1]
	s_waitcnt vmcnt(12)
	v_pk_fma_f32 v[62:63], v[86:87], v[82:83], v[62:63] op_sel_hi:[1,0,1]
	v_pk_fma_f32 v[60:61], v[88:89], v[82:83], v[60:61] op_sel_hi:[1,0,1]
	v_mov_b32_e32 v82, v109
	v_pk_fma_f32 v[76:77], v[80:81], v[76:77], v[126:127] op_sel_hi:[1,0,1]
	v_pk_fma_f32 v[64:65], v[84:85], v[70:71], v[64:65] op_sel_hi:[1,0,1]
	v_pk_fma_f32 v[70:71], v[84:85], v[114:115], v[72:73] op_sel_hi:[1,0,1]
	v_pk_fma_f32 v[68:69], v[86:87], v[82:83], v[68:69] op_sel_hi:[1,0,1]
	v_pk_fma_f32 v[82:83], v[88:89], v[82:83], v[66:67] op_sel_hi:[1,0,1]
	v_mov_b32_e32 v66, v115
	v_pk_fma_f32 v[72:73], v[84:85], v[122:123], v[76:77] op_sel_hi:[1,0,1]
	v_pk_fma_f32 v[58:59], v[86:87], v[66:67], v[58:59] op_sel_hi:[1,0,1]
	v_pk_fma_f32 v[70:71], v[88:89], v[66:67], v[70:71] op_sel_hi:[1,0,1]
	v_mov_b32_e32 v66, v123
	v_pk_fma_f32 v[100:101], v[80:81], v[100:101], v[140:141] op_sel_hi:[1,0,1]
	v_pk_fma_f32 v[40:41], v[84:85], v[130:131], v[40:41] op_sel_hi:[1,0,1]
	v_pk_fma_f32 v[56:57], v[86:87], v[66:67], v[56:57] op_sel_hi:[1,0,1]
	v_pk_fma_f32 v[72:73], v[88:89], v[66:67], v[72:73] op_sel_hi:[1,0,1]
	v_mov_b32_e32 v66, v131
	v_pk_fma_f32 v[106:107], v[80:81], v[106:107], v[148:149] op_sel_hi:[1,0,1]
	v_pk_fma_f32 v[76:77], v[84:85], v[136:137], v[100:101] op_sel_hi:[1,0,1]
	v_pk_fma_f32 v[42:43], v[86:87], v[66:67], v[42:43] op_sel_hi:[1,0,1]
	v_pk_fma_f32 v[40:41], v[88:89], v[66:67], v[40:41] op_sel_hi:[1,0,1]
	v_mov_b32_e32 v66, v137
	v_pk_fma_f32 v[32:33], v[80:81], v[112:113], v[32:33] op_sel_hi:[1,0,1]
	v_pk_fma_f32 v[80:81], v[84:85], v[144:145], v[106:107] op_sel_hi:[1,0,1]
	v_pk_fma_f32 v[38:39], v[86:87], v[66:67], v[38:39] op_sel_hi:[1,0,1]
	v_pk_fma_f32 v[76:77], v[88:89], v[66:67], v[76:77] op_sel_hi:[1,0,1]
	v_mov_b32_e32 v66, v145
	v_pk_fma_f32 v[32:33], v[84:85], v[152:153], v[32:33] op_sel_hi:[1,0,1]
	v_pk_fma_f32 v[36:37], v[86:87], v[66:67], v[36:37] op_sel_hi:[1,0,1]
	v_pk_fma_f32 v[80:81], v[88:89], v[66:67], v[80:81] op_sel_hi:[1,0,1]
	v_mov_b32_e32 v66, v153
	v_pk_fma_f32 v[32:33], v[88:89], v[66:67], v[32:33] op_sel_hi:[1,0,1]
	v_pk_fma_f32 v[34:35], v[86:87], v[66:67], v[34:35] op_sel_hi:[1,0,1]
	v_pk_fma_f32 v[66:67], v[86:87], v[74:75], v[78:79] op_sel_hi:[1,0,1]
	v_pk_fma_f32 v[74:75], v[88:89], v[74:75], v[64:65] op_sel_hi:[1,0,1]
	s_waitcnt vmcnt(11)
	v_pk_fma_f32 v[62:63], v[90:91], v[104:105], v[62:63] op_sel_hi:[1,0,1]
	v_pk_fma_f32 v[60:61], v[92:93], v[104:105], v[60:61] op_sel_hi:[1,0,1]
	s_waitcnt lgkmcnt(1)
	v_pk_fma_f32 v[78:79], v[92:93], v[54:55], v[32:33] op_sel_hi:[1,0,1]
	v_mov_b32_e32 v32, v105
	v_pk_fma_f32 v[64:65], v[90:91], v[94:95], v[66:67] op_sel_hi:[1,0,1]
	v_pk_fma_f32 v[66:67], v[92:93], v[94:95], v[74:75] op_sel_hi:[1,0,1]
	v_pk_fma_f32 v[68:69], v[90:91], v[110:111], v[68:69] op_sel_hi:[1,0,1]
	v_pk_fma_f32 v[82:83], v[92:93], v[110:111], v[82:83] op_sel_hi:[1,0,1]
	v_pk_fma_f32 v[86:87], v[92:93], v[124:125], v[72:73] op_sel_hi:[1,0,1]
	s_waitcnt vmcnt(10)
	v_pk_fma_f32 v[72:73], v[10:11], v[32:33], v[62:63] op_sel_hi:[1,0,1]
	v_pk_fma_f32 v[74:75], v[12:13], v[32:33], v[60:61] op_sel_hi:[1,0,1]
	v_mov_b32_e32 v32, v111
	v_pk_fma_f32 v[58:59], v[90:91], v[116:117], v[58:59] op_sel_hi:[1,0,1]
	v_pk_fma_f32 v[84:85], v[92:93], v[116:117], v[70:71] op_sel_hi:[1,0,1]
	v_pk_fma_f32 v[68:69], v[10:11], v[32:33], v[68:69] op_sel_hi:[1,0,1]
	v_pk_fma_f32 v[70:71], v[12:13], v[32:33], v[82:83] op_sel_hi:[1,0,1]
	v_mov_b32_e32 v32, v117
	v_pk_fma_f32 v[56:57], v[90:91], v[124:125], v[56:57] op_sel_hi:[1,0,1]
	v_pk_fma_f32 v[42:43], v[90:91], v[132:133], v[42:43] op_sel_hi:[1,0,1]
	v_pk_fma_f32 v[40:41], v[92:93], v[132:133], v[40:41] op_sel_hi:[1,0,1]
	v_pk_fma_f32 v[88:89], v[92:93], v[138:139], v[76:77] op_sel_hi:[1,0,1]
	v_pk_fma_f32 v[76:77], v[90:91], v[54:55], v[34:35] op_sel_hi:[1,0,1]
	v_pk_fma_f32 v[60:61], v[10:11], v[32:33], v[58:59] op_sel_hi:[1,0,1]
	v_pk_fma_f32 v[62:63], v[12:13], v[32:33], v[84:85] op_sel_hi:[1,0,1]
	v_mov_b32_e32 v32, v125
	v_mov_b32_e32 v34, v133
	v_pk_fma_f32 v[38:39], v[90:91], v[138:139], v[38:39] op_sel_hi:[1,0,1]
	v_pk_fma_f32 v[94:95], v[90:91], v[146:147], v[36:37] op_sel_hi:[1,0,1]
	v_pk_fma_f32 v[80:81], v[92:93], v[146:147], v[80:81] op_sel_hi:[1,0,1]
	v_pk_fma_f32 v[56:57], v[10:11], v[32:33], v[56:57] op_sel_hi:[1,0,1]
	v_pk_fma_f32 v[58:59], v[12:13], v[32:33], v[86:87] op_sel_hi:[1,0,1]
	v_pk_fma_f32 v[32:33], v[10:11], v[34:35], v[42:43] op_sel_hi:[1,0,1]
	v_pk_fma_f32 v[34:35], v[12:13], v[34:35], v[40:41] op_sel_hi:[1,0,1]
	v_mov_b32_e32 v40, v139
	v_mov_b32_e32 v42, v147
	v_pk_fma_f32 v[36:37], v[10:11], v[40:41], v[38:39] op_sel_hi:[1,0,1]
	v_pk_fma_f32 v[38:39], v[12:13], v[40:41], v[88:89] op_sel_hi:[1,0,1]
	v_pk_fma_f32 v[40:41], v[10:11], v[42:43], v[94:95] op_sel_hi:[1,0,1]
	v_pk_fma_f32 v[42:43], v[12:13], v[42:43], v[80:81] op_sel_hi:[1,0,1]
	v_mov_b32_e32 v80, v55
	v_pk_fma_f32 v[54:55], v[10:11], v[80:81], v[76:77] op_sel_hi:[1,0,1]
	v_pk_fma_f32 v[76:77], v[12:13], v[80:81], v[78:79] op_sel_hi:[1,0,1]
	v_pk_fma_f32 v[10:11], v[10:11], v[52:53], v[64:65] op_sel_hi:[1,0,1]
	v_pk_fma_f32 v[12:13], v[12:13], v[52:53], v[66:67] op_sel_hi:[1,0,1]
	v_mov_b32_e32 v78, v51
	v_mov_b32_e32 v66, v49
	v_mov_b32_e32 v64, v47
	v_mov_b32_e32 v52, v45
	s_waitcnt vmcnt(9)
	v_pk_fma_f32 v[72:73], v[6:7], v[50:51], v[72:73] op_sel_hi:[1,0,1]
	v_pk_fma_f32 v[74:75], v[8:9], v[50:51], v[74:75] op_sel_hi:[1,0,1]
	v_mov_b32_e32 v50, v25
	v_pk_fma_f32 v[68:69], v[6:7], v[48:49], v[68:69] op_sel_hi:[1,0,1]
	v_pk_fma_f32 v[70:71], v[8:9], v[48:49], v[70:71] op_sel_hi:[1,0,1]
	v_mov_b32_e32 v48, v27
	v_pk_fma_f32 v[60:61], v[6:7], v[46:47], v[60:61] op_sel_hi:[1,0,1]
	v_pk_fma_f32 v[62:63], v[8:9], v[46:47], v[62:63] op_sel_hi:[1,0,1]
	v_mov_b32_e32 v46, v29
	v_pk_fma_f32 v[56:57], v[6:7], v[44:45], v[56:57] op_sel_hi:[1,0,1]
	v_pk_fma_f32 v[82:83], v[8:9], v[44:45], v[58:59] op_sel_hi:[1,0,1]
	s_waitcnt lgkmcnt(0)
	v_mov_b32_e32 v80, v31
	v_pk_fma_f32 v[32:33], v[6:7], v[24:25], v[32:33] op_sel_hi:[1,0,1]
	v_pk_fma_f32 v[24:25], v[8:9], v[24:25], v[34:35] op_sel_hi:[1,0,1]
	v_pk_fma_f32 v[34:35], v[6:7], v[26:27], v[36:37] op_sel_hi:[1,0,1]
	v_pk_fma_f32 v[26:27], v[8:9], v[26:27], v[38:39] op_sel_hi:[1,0,1]
	v_pk_fma_f32 v[36:37], v[6:7], v[28:29], v[40:41] op_sel_hi:[1,0,1]
	v_pk_fma_f32 v[84:85], v[8:9], v[28:29], v[42:43] op_sel_hi:[1,0,1]
	v_pk_fma_f32 v[86:87], v[6:7], v[30:31], v[54:55] op_sel_hi:[1,0,1]
	v_pk_fma_f32 v[88:89], v[8:9], v[30:31], v[76:77] op_sel_hi:[1,0,1]
	v_pk_fma_f32 v[6:7], v[6:7], v[22:23], v[10:11] op_sel_hi:[1,0,1]
	v_pk_fma_f32 v[8:9], v[8:9], v[22:23], v[12:13] op_sel_hi:[1,0,1]
	s_waitcnt vmcnt(8)
	v_pk_fma_f32 v[76:77], v[2:3], v[78:79], v[72:73] op_sel_hi:[1,0,1]
	v_pk_fma_f32 v[72:73], v[4:5], v[78:79], v[74:75] op_sel_hi:[1,0,1]
	v_pk_fma_f32 v[68:69], v[2:3], v[66:67], v[68:69] op_sel_hi:[1,0,1]
	v_pk_fma_f32 v[66:67], v[4:5], v[66:67], v[70:71] op_sel_hi:[1,0,1]
	v_pk_fma_f32 v[58:59], v[2:3], v[64:65], v[60:61] op_sel_hi:[1,0,1]
	v_pk_fma_f32 v[44:45], v[4:5], v[64:65], v[62:63] op_sel_hi:[1,0,1]
	v_pk_fma_f32 v[56:57], v[2:3], v[52:53], v[56:57] op_sel_hi:[1,0,1]
	v_pk_fma_f32 v[54:55], v[4:5], v[52:53], v[82:83] op_sel_hi:[1,0,1]
	v_pk_fma_f32 v[42:43], v[2:3], v[50:51], v[32:33] op_sel_hi:[1,0,1]
	v_pk_fma_f32 v[40:41], v[4:5], v[50:51], v[24:25] op_sel_hi:[1,0,1]
	v_pk_fma_f32 v[38:39], v[2:3], v[48:49], v[34:35] op_sel_hi:[1,0,1]
	v_pk_fma_f32 v[28:29], v[4:5], v[48:49], v[26:27] op_sel_hi:[1,0,1]
	v_pk_fma_f32 v[36:37], v[2:3], v[46:47], v[36:37] op_sel_hi:[1,0,1]
	v_pk_fma_f32 v[30:31], v[4:5], v[46:47], v[84:85] op_sel_hi:[1,0,1]
	v_pk_fma_f32 v[34:35], v[2:3], v[80:81], v[86:87] op_sel_hi:[1,0,1]
	v_pk_fma_f32 v[32:33], v[4:5], v[80:81], v[88:89] op_sel_hi:[1,0,1]
	v_pk_fma_f32 v[26:27], v[2:3], v[0:1], v[6:7] op_sel_hi:[1,0,1]
	v_pk_fma_f32 v[24:25], v[4:5], v[0:1], v[8:9] op_sel_hi:[1,0,1]
	s_cbranch_scc0 .LBB0_417
	s_mov_b32 s5, 0xfeb00000
	v_add_co_u32_e64 v2, s[42:43], s5, v20
	s_mov_b32 s5, 0xfee00000
	s_nop 0
	v_addc_co_u32_e64 v3, s[42:43], -1, v21, s[42:43]
	v_add_co_u32_e64 v4, s[42:43], s5, v20
	s_mov_b32 s5, 0xff100000
	s_nop 0
	v_addc_co_u32_e64 v5, s[42:43], -1, v21, s[42:43]
	v_add_co_u32_e64 v6, s[42:43], s5, v20
	s_mov_b32 s5, 0xff400000
	s_nop 0
	v_addc_co_u32_e64 v7, s[42:43], -1, v21, s[42:43]
	v_add_co_u32_e64 v8, s[42:43], s5, v20
	s_mov_b32 s5, 0xff700000
	s_nop 0
	v_addc_co_u32_e64 v9, s[42:43], -1, v21, s[42:43]
	v_add_co_u32_e64 v10, s[42:43], s5, v20
	s_mov_b32 s5, 0xffa00000
	s_nop 0
	v_addc_co_u32_e64 v11, s[42:43], -1, v21, s[42:43]
	v_add_co_u32_e64 v12, s[42:43], s5, v20
	s_mov_b32 s5, 0xffd00000
	s_nop 0
	v_addc_co_u32_e64 v13, s[42:43], -1, v21, s[42:43]
	v_add_co_u32_e64 v46, s[42:43], s5, v20
	v_add_u32_e32 v65, s4, v17
	s_nop 0
	v_addc_co_u32_e64 v47, s[42:43], -1, v21, s[42:43]
	global_load_dwordx4 v[60:63], v[2:3], off
	global_load_dwordx4 v[78:81], v[4:5], off
	global_load_dwordx4 v[82:85], v[6:7], off
	global_load_dwordx4 v[86:89], v[8:9], off
	global_load_dwordx4 v[90:93], v[10:11], off
	s_nop 0
	global_load_dwordx4 v[10:13], v[12:13], off
	s_nop 0
	global_load_dwordx4 v[6:9], v[46:47], off
	global_load_dwordx4 v[2:5], v[20:21], off
	v_add_u32_e32 v0, 0x10000, v65
	v_add_u32_e32 v22, 0x10100, v65
	v_add_u32_e32 v47, 0x10200, v65
	v_add_u32_e32 v48, 0x10300, v65
	v_add_u32_e32 v49, 0x10400, v65
	v_add_u32_e32 v50, 0x10500, v65
	v_add_u32_e32 v51, 0x10600, v65
	v_add_u32_e32 v71, 0x10700, v65
	ds_read_b32 v46, v0
	ds_read_b32 v64, v22
	ds_read_b32 v70, v47
	ds_read_b32 v74, v48
	ds_read_b32 v94, v49
	ds_read_b32 v52, v50
	ds_read_b32 v22, v51
	ds_read_b32 v0, v71
	ds_read2st64_b32 v[100:101], v65 offset1:1
	ds_read2st64_b32 v[102:103], v65 offset0:2 offset1:3
	ds_read2st64_b32 v[104:105], v65 offset0:4 offset1:5
	ds_read2st64_b32 v[50:51], v65 offset0:6 offset1:7
	ds_read2st64_b32 v[106:107], v65 offset0:32 offset1:33
	ds_read2st64_b32 v[108:109], v65 offset0:34 offset1:35
	ds_read2st64_b32 v[110:111], v65 offset0:36 offset1:37
	ds_read2st64_b32 v[48:49], v65 offset0:38 offset1:39
	s_addk_i32 s4, 0x800
	s_mov_b64 s[8:9], 0x1800000
	v_lshl_add_u64 v[20:21], v[20:21], 0, s[8:9]
	s_cmpk_eq_i32 s4, 0x2000
	s_waitcnt vmcnt(7) lgkmcnt(14)
	v_pk_fma_f32 v[96:97], v[60:61], v[46:47], v[26:27] op_sel_hi:[1,0,1]
	v_pk_fma_f32 v[98:99], v[62:63], v[46:47], v[24:25] op_sel_hi:[1,0,1]
	ds_read2st64_b32 v[112:113], v65 offset0:64 offset1:65
	ds_read2st64_b32 v[114:115], v65 offset0:66 offset1:67
	ds_read2st64_b32 v[116:117], v65 offset0:68 offset1:69
	ds_read2st64_b32 v[46:47], v65 offset0:70 offset1:71
	s_waitcnt lgkmcnt(11)
	v_pk_fma_f32 v[76:77], v[60:61], v[100:101], v[76:77] op_sel_hi:[1,0,1]
	s_waitcnt lgkmcnt(3)
	v_pk_fma_f32 v[118:119], v[62:63], v[112:113], v[44:45] op_sel_hi:[1,0,1]
	ds_read2st64_b32 v[120:121], v65 offset0:96 offset1:97
	ds_read2st64_b32 v[122:123], v65 offset0:98 offset1:99
	ds_read2st64_b32 v[124:125], v65 offset0:100 offset1:101
	ds_read2st64_b32 v[44:45], v65 offset0:102 offset1:103
	ds_read2st64_b32 v[128:129], v65 offset0:128 offset1:129
	ds_read2st64_b32 v[130:131], v65 offset0:130 offset1:131
	ds_read2st64_b32 v[132:133], v65 offset0:132 offset1:133
	ds_read2st64_b32 v[24:25], v65 offset0:134 offset1:135
	ds_read2st64_b32 v[134:135], v65 offset0:160 offset1:161
	ds_read2st64_b32 v[136:137], v65 offset0:162 offset1:163
	ds_read2st64_b32 v[138:139], v65 offset0:164 offset1:165
	ds_read2st64_b32 v[26:27], v65 offset0:166 offset1:167
	s_waitcnt lgkmcnt(11)
	v_pk_fma_f32 v[126:127], v[62:63], v[120:121], v[54:55] op_sel_hi:[1,0,1]
	s_waitcnt lgkmcnt(3)
	v_pk_fma_f32 v[140:141], v[62:63], v[134:135], v[28:29] op_sel_hi:[1,0,1]
	ds_read2st64_b32 v[142:143], v65 offset0:192 offset1:193
	ds_read2st64_b32 v[144:145], v65 offset0:194 offset1:195
	ds_read2st64_b32 v[146:147], v65 offset0:196 offset1:197
	ds_read2st64_b32 v[28:29], v65 offset0:198 offset1:199
	v_pk_fma_f32 v[72:73], v[62:63], v[100:101], v[72:73] op_sel_hi:[1,0,1]
	s_waitcnt lgkmcnt(3)
	v_pk_fma_f32 v[148:149], v[62:63], v[142:143], v[30:31] op_sel_hi:[1,0,1]
	ds_read2st64_b32 v[150:151], v65 offset0:224 offset1:225
	ds_read2st64_b32 v[152:153], v65 offset0:226 offset1:227
	ds_read2st64_b32 v[54:55], v65 offset0:228 offset1:229
	ds_read2st64_b32 v[30:31], v65 offset0:230 offset1:231
	v_pk_fma_f32 v[68:69], v[60:61], v[106:107], v[68:69] op_sel_hi:[1,0,1]
	v_pk_fma_f32 v[58:59], v[60:61], v[112:113], v[58:59] op_sel_hi:[1,0,1]
	v_pk_fma_f32 v[56:57], v[60:61], v[120:121], v[56:57] op_sel_hi:[1,0,1]
	v_pk_fma_f32 v[42:43], v[60:61], v[128:129], v[42:43] op_sel_hi:[1,0,1]
	v_pk_fma_f32 v[38:39], v[60:61], v[134:135], v[38:39] op_sel_hi:[1,0,1]
	v_pk_fma_f32 v[36:37], v[60:61], v[142:143], v[36:37] op_sel_hi:[1,0,1]
	s_waitcnt lgkmcnt(3)
	v_pk_fma_f32 v[34:35], v[60:61], v[150:151], v[34:35] op_sel_hi:[1,0,1]
	v_mov_b32_e32 v60, v101
	v_pk_fma_f32 v[66:67], v[62:63], v[106:107], v[66:67] op_sel_hi:[1,0,1]
	v_pk_fma_f32 v[40:41], v[62:63], v[128:129], v[40:41] op_sel_hi:[1,0,1]
	v_pk_fma_f32 v[32:33], v[62:63], v[150:151], v[32:33] op_sel_hi:[1,0,1]
	s_waitcnt vmcnt(6)
	v_pk_fma_f32 v[62:63], v[78:79], v[60:61], v[76:77] op_sel_hi:[1,0,1]
	v_pk_fma_f32 v[60:61], v[80:81], v[60:61], v[72:73] op_sel_hi:[1,0,1]
	v_mov_b32_e32 v72, v107
	v_mov_b32_e32 v100, v129
	v_pk_fma_f32 v[68:69], v[78:79], v[72:73], v[68:69] op_sel_hi:[1,0,1]
	v_pk_fma_f32 v[66:67], v[80:81], v[72:73], v[66:67] op_sel_hi:[1,0,1]
	v_mov_b32_e32 v72, v113
	v_mov_b32_e32 v76, v121
	v_pk_fma_f32 v[42:43], v[78:79], v[100:101], v[42:43] op_sel_hi:[1,0,1]
	v_pk_fma_f32 v[40:41], v[80:81], v[100:101], v[40:41] op_sel_hi:[1,0,1]
	v_mov_b32_e32 v100, v135
	v_mov_b32_e32 v106, v143
	v_mov_b32_e32 v112, v151
	v_pk_fma_f32 v[58:59], v[78:79], v[72:73], v[58:59] op_sel_hi:[1,0,1]
	v_pk_fma_f32 v[56:57], v[78:79], v[76:77], v[56:57] op_sel_hi:[1,0,1]
	v_pk_fma_f32 v[38:39], v[78:79], v[100:101], v[38:39] op_sel_hi:[1,0,1]
	v_pk_fma_f32 v[36:37], v[78:79], v[106:107], v[36:37] op_sel_hi:[1,0,1]
	v_pk_fma_f32 v[34:35], v[78:79], v[112:113], v[34:35] op_sel_hi:[1,0,1]
	v_pk_fma_f32 v[78:79], v[78:79], v[64:65], v[96:97] op_sel_hi:[1,0,1]
	s_waitcnt vmcnt(5)
	v_pk_fma_f32 v[62:63], v[82:83], v[102:103], v[62:63] op_sel_hi:[1,0,1]
	v_pk_fma_f32 v[78:79], v[82:83], v[70:71], v[78:79] op_sel_hi:[1,0,1]
	v_pk_fma_f32 v[60:61], v[84:85], v[102:103], v[60:61] op_sel_hi:[1,0,1]
	v_pk_fma_f32 v[68:69], v[82:83], v[108:109], v[68:69] op_sel_hi:[1,0,1]
	v_pk_fma_f32 v[58:59], v[82:83], v[114:115], v[58:59] op_sel_hi:[1,0,1]
	v_pk_fma_f32 v[56:57], v[82:83], v[122:123], v[56:57] op_sel_hi:[1,0,1]
	v_pk_fma_f32 v[42:43], v[82:83], v[130:131], v[42:43] op_sel_hi:[1,0,1]
	v_pk_fma_f32 v[38:39], v[82:83], v[136:137], v[38:39] op_sel_hi:[1,0,1]
	v_pk_fma_f32 v[36:37], v[82:83], v[144:145], v[36:37] op_sel_hi:[1,0,1]
	s_waitcnt lgkmcnt(2)
	v_pk_fma_f32 v[34:35], v[82:83], v[152:153], v[34:35] op_sel_hi:[1,0,1]
	v_mov_b32_e32 v82, v103
	v_pk_fma_f32 v[72:73], v[80:81], v[72:73], v[118:119] op_sel_hi:[1,0,1]
	v_pk_fma_f32 v[64:65], v[80:81], v[64:65], v[98:99] op_sel_hi:[1,0,1]
	v_pk_fma_f32 v[66:67], v[84:85], v[108:109], v[66:67] op_sel_hi:[1,0,1]
	s_waitcnt vmcnt(4)
	v_pk_fma_f32 v[62:63], v[86:87], v[82:83], v[62:63] op_sel_hi:[1,0,1]
	v_pk_fma_f32 v[60:61], v[88:89], v[82:83], v[60:61] op_sel_hi:[1,0,1]
	v_mov_b32_e32 v82, v109
	v_pk_fma_f32 v[76:77], v[80:81], v[76:77], v[126:127] op_sel_hi:[1,0,1]
	v_pk_fma_f32 v[64:65], v[84:85], v[70:71], v[64:65] op_sel_hi:[1,0,1]
	v_pk_fma_f32 v[70:71], v[84:85], v[114:115], v[72:73] op_sel_hi:[1,0,1]
	v_pk_fma_f32 v[68:69], v[86:87], v[82:83], v[68:69] op_sel_hi:[1,0,1]
	v_pk_fma_f32 v[82:83], v[88:89], v[82:83], v[66:67] op_sel_hi:[1,0,1]
	v_mov_b32_e32 v66, v115
	v_pk_fma_f32 v[72:73], v[84:85], v[122:123], v[76:77] op_sel_hi:[1,0,1]
	v_pk_fma_f32 v[58:59], v[86:87], v[66:67], v[58:59] op_sel_hi:[1,0,1]
	v_pk_fma_f32 v[70:71], v[88:89], v[66:67], v[70:71] op_sel_hi:[1,0,1]
	v_mov_b32_e32 v66, v123
	v_pk_fma_f32 v[100:101], v[80:81], v[100:101], v[140:141] op_sel_hi:[1,0,1]
	v_pk_fma_f32 v[40:41], v[84:85], v[130:131], v[40:41] op_sel_hi:[1,0,1]
	v_pk_fma_f32 v[56:57], v[86:87], v[66:67], v[56:57] op_sel_hi:[1,0,1]
	v_pk_fma_f32 v[72:73], v[88:89], v[66:67], v[72:73] op_sel_hi:[1,0,1]
	v_mov_b32_e32 v66, v131
	v_pk_fma_f32 v[106:107], v[80:81], v[106:107], v[148:149] op_sel_hi:[1,0,1]
	v_pk_fma_f32 v[76:77], v[84:85], v[136:137], v[100:101] op_sel_hi:[1,0,1]
	v_pk_fma_f32 v[42:43], v[86:87], v[66:67], v[42:43] op_sel_hi:[1,0,1]
	v_pk_fma_f32 v[40:41], v[88:89], v[66:67], v[40:41] op_sel_hi:[1,0,1]
	v_mov_b32_e32 v66, v137
	v_pk_fma_f32 v[32:33], v[80:81], v[112:113], v[32:33] op_sel_hi:[1,0,1]
	v_pk_fma_f32 v[80:81], v[84:85], v[144:145], v[106:107] op_sel_hi:[1,0,1]
	v_pk_fma_f32 v[38:39], v[86:87], v[66:67], v[38:39] op_sel_hi:[1,0,1]
	v_pk_fma_f32 v[76:77], v[88:89], v[66:67], v[76:77] op_sel_hi:[1,0,1]
	v_mov_b32_e32 v66, v145
	v_pk_fma_f32 v[32:33], v[84:85], v[152:153], v[32:33] op_sel_hi:[1,0,1]
	v_pk_fma_f32 v[36:37], v[86:87], v[66:67], v[36:37] op_sel_hi:[1,0,1]
	v_pk_fma_f32 v[80:81], v[88:89], v[66:67], v[80:81] op_sel_hi:[1,0,1]
	v_mov_b32_e32 v66, v153
	v_pk_fma_f32 v[32:33], v[88:89], v[66:67], v[32:33] op_sel_hi:[1,0,1]
	v_pk_fma_f32 v[34:35], v[86:87], v[66:67], v[34:35] op_sel_hi:[1,0,1]
	v_pk_fma_f32 v[66:67], v[86:87], v[74:75], v[78:79] op_sel_hi:[1,0,1]
	v_pk_fma_f32 v[74:75], v[88:89], v[74:75], v[64:65] op_sel_hi:[1,0,1]
	s_waitcnt vmcnt(3)
	v_pk_fma_f32 v[62:63], v[90:91], v[104:105], v[62:63] op_sel_hi:[1,0,1]
	v_pk_fma_f32 v[60:61], v[92:93], v[104:105], v[60:61] op_sel_hi:[1,0,1]
	s_waitcnt lgkmcnt(1)
	v_pk_fma_f32 v[78:79], v[92:93], v[54:55], v[32:33] op_sel_hi:[1,0,1]
	v_mov_b32_e32 v32, v105
	v_pk_fma_f32 v[64:65], v[90:91], v[94:95], v[66:67] op_sel_hi:[1,0,1]
	v_pk_fma_f32 v[66:67], v[92:93], v[94:95], v[74:75] op_sel_hi:[1,0,1]
	v_pk_fma_f32 v[68:69], v[90:91], v[110:111], v[68:69] op_sel_hi:[1,0,1]
	v_pk_fma_f32 v[82:83], v[92:93], v[110:111], v[82:83] op_sel_hi:[1,0,1]
	v_pk_fma_f32 v[86:87], v[92:93], v[124:125], v[72:73] op_sel_hi:[1,0,1]
	s_waitcnt vmcnt(2)
	v_pk_fma_f32 v[72:73], v[10:11], v[32:33], v[62:63] op_sel_hi:[1,0,1]
	v_pk_fma_f32 v[74:75], v[12:13], v[32:33], v[60:61] op_sel_hi:[1,0,1]
	v_mov_b32_e32 v32, v111
	v_pk_fma_f32 v[58:59], v[90:91], v[116:117], v[58:59] op_sel_hi:[1,0,1]
	v_pk_fma_f32 v[84:85], v[92:93], v[116:117], v[70:71] op_sel_hi:[1,0,1]
	v_pk_fma_f32 v[68:69], v[10:11], v[32:33], v[68:69] op_sel_hi:[1,0,1]
	v_pk_fma_f32 v[70:71], v[12:13], v[32:33], v[82:83] op_sel_hi:[1,0,1]
	v_mov_b32_e32 v32, v117
	v_pk_fma_f32 v[56:57], v[90:91], v[124:125], v[56:57] op_sel_hi:[1,0,1]
	v_pk_fma_f32 v[42:43], v[90:91], v[132:133], v[42:43] op_sel_hi:[1,0,1]
	v_pk_fma_f32 v[40:41], v[92:93], v[132:133], v[40:41] op_sel_hi:[1,0,1]
	v_pk_fma_f32 v[88:89], v[92:93], v[138:139], v[76:77] op_sel_hi:[1,0,1]
	v_pk_fma_f32 v[76:77], v[90:91], v[54:55], v[34:35] op_sel_hi:[1,0,1]
	v_pk_fma_f32 v[60:61], v[10:11], v[32:33], v[58:59] op_sel_hi:[1,0,1]
	v_pk_fma_f32 v[62:63], v[12:13], v[32:33], v[84:85] op_sel_hi:[1,0,1]
	v_mov_b32_e32 v32, v125
	v_mov_b32_e32 v34, v133
	v_pk_fma_f32 v[38:39], v[90:91], v[138:139], v[38:39] op_sel_hi:[1,0,1]
	v_pk_fma_f32 v[94:95], v[90:91], v[146:147], v[36:37] op_sel_hi:[1,0,1]
	v_pk_fma_f32 v[80:81], v[92:93], v[146:147], v[80:81] op_sel_hi:[1,0,1]
	v_pk_fma_f32 v[56:57], v[10:11], v[32:33], v[56:57] op_sel_hi:[1,0,1]
	v_pk_fma_f32 v[58:59], v[12:13], v[32:33], v[86:87] op_sel_hi:[1,0,1]
	v_pk_fma_f32 v[32:33], v[10:11], v[34:35], v[42:43] op_sel_hi:[1,0,1]
	v_pk_fma_f32 v[34:35], v[12:13], v[34:35], v[40:41] op_sel_hi:[1,0,1]
	v_mov_b32_e32 v40, v139
	v_mov_b32_e32 v42, v147
	v_pk_fma_f32 v[36:37], v[10:11], v[40:41], v[38:39] op_sel_hi:[1,0,1]
	v_pk_fma_f32 v[38:39], v[12:13], v[40:41], v[88:89] op_sel_hi:[1,0,1]
	v_pk_fma_f32 v[40:41], v[10:11], v[42:43], v[94:95] op_sel_hi:[1,0,1]
	v_pk_fma_f32 v[42:43], v[12:13], v[42:43], v[80:81] op_sel_hi:[1,0,1]
	v_mov_b32_e32 v80, v55
	v_pk_fma_f32 v[54:55], v[10:11], v[80:81], v[76:77] op_sel_hi:[1,0,1]
	v_pk_fma_f32 v[76:77], v[12:13], v[80:81], v[78:79] op_sel_hi:[1,0,1]
	v_pk_fma_f32 v[10:11], v[10:11], v[52:53], v[64:65] op_sel_hi:[1,0,1]
	v_pk_fma_f32 v[12:13], v[12:13], v[52:53], v[66:67] op_sel_hi:[1,0,1]
	v_mov_b32_e32 v78, v51
	v_mov_b32_e32 v66, v49
	v_mov_b32_e32 v64, v47
	v_mov_b32_e32 v52, v45
	s_waitcnt vmcnt(1)
	v_pk_fma_f32 v[72:73], v[6:7], v[50:51], v[72:73] op_sel_hi:[1,0,1]
	v_pk_fma_f32 v[74:75], v[8:9], v[50:51], v[74:75] op_sel_hi:[1,0,1]
	v_mov_b32_e32 v50, v25
	v_pk_fma_f32 v[68:69], v[6:7], v[48:49], v[68:69] op_sel_hi:[1,0,1]
	v_pk_fma_f32 v[70:71], v[8:9], v[48:49], v[70:71] op_sel_hi:[1,0,1]
	v_mov_b32_e32 v48, v27
	v_pk_fma_f32 v[60:61], v[6:7], v[46:47], v[60:61] op_sel_hi:[1,0,1]
	v_pk_fma_f32 v[62:63], v[8:9], v[46:47], v[62:63] op_sel_hi:[1,0,1]
	v_mov_b32_e32 v46, v29
	v_pk_fma_f32 v[56:57], v[6:7], v[44:45], v[56:57] op_sel_hi:[1,0,1]
	v_pk_fma_f32 v[82:83], v[8:9], v[44:45], v[58:59] op_sel_hi:[1,0,1]
	s_waitcnt lgkmcnt(0)
	v_mov_b32_e32 v80, v31
	v_pk_fma_f32 v[32:33], v[6:7], v[24:25], v[32:33] op_sel_hi:[1,0,1]
	v_pk_fma_f32 v[24:25], v[8:9], v[24:25], v[34:35] op_sel_hi:[1,0,1]
	v_pk_fma_f32 v[34:35], v[6:7], v[26:27], v[36:37] op_sel_hi:[1,0,1]
	v_pk_fma_f32 v[26:27], v[8:9], v[26:27], v[38:39] op_sel_hi:[1,0,1]
	v_pk_fma_f32 v[36:37], v[6:7], v[28:29], v[40:41] op_sel_hi:[1,0,1]
	v_pk_fma_f32 v[84:85], v[8:9], v[28:29], v[42:43] op_sel_hi:[1,0,1]
	v_pk_fma_f32 v[86:87], v[6:7], v[30:31], v[54:55] op_sel_hi:[1,0,1]
	v_pk_fma_f32 v[88:89], v[8:9], v[30:31], v[76:77] op_sel_hi:[1,0,1]
	v_pk_fma_f32 v[6:7], v[6:7], v[22:23], v[10:11] op_sel_hi:[1,0,1]
	v_pk_fma_f32 v[8:9], v[8:9], v[22:23], v[12:13] op_sel_hi:[1,0,1]
	s_waitcnt vmcnt(0)
	v_pk_fma_f32 v[76:77], v[2:3], v[78:79], v[72:73] op_sel_hi:[1,0,1]
	v_pk_fma_f32 v[72:73], v[4:5], v[78:79], v[74:75] op_sel_hi:[1,0,1]
	v_pk_fma_f32 v[68:69], v[2:3], v[66:67], v[68:69] op_sel_hi:[1,0,1]
	v_pk_fma_f32 v[66:67], v[4:5], v[66:67], v[70:71] op_sel_hi:[1,0,1]
	v_pk_fma_f32 v[58:59], v[2:3], v[64:65], v[60:61] op_sel_hi:[1,0,1]
	v_pk_fma_f32 v[44:45], v[4:5], v[64:65], v[62:63] op_sel_hi:[1,0,1]
	v_pk_fma_f32 v[56:57], v[2:3], v[52:53], v[56:57] op_sel_hi:[1,0,1]
	v_pk_fma_f32 v[54:55], v[4:5], v[52:53], v[82:83] op_sel_hi:[1,0,1]
	v_pk_fma_f32 v[42:43], v[2:3], v[50:51], v[32:33] op_sel_hi:[1,0,1]
	v_pk_fma_f32 v[40:41], v[4:5], v[50:51], v[24:25] op_sel_hi:[1,0,1]
	v_pk_fma_f32 v[38:39], v[2:3], v[48:49], v[34:35] op_sel_hi:[1,0,1]
	v_pk_fma_f32 v[28:29], v[4:5], v[48:49], v[26:27] op_sel_hi:[1,0,1]
	v_pk_fma_f32 v[36:37], v[2:3], v[46:47], v[36:37] op_sel_hi:[1,0,1]
	v_pk_fma_f32 v[30:31], v[4:5], v[46:47], v[84:85] op_sel_hi:[1,0,1]
	v_pk_fma_f32 v[34:35], v[2:3], v[80:81], v[86:87] op_sel_hi:[1,0,1]
	v_pk_fma_f32 v[32:33], v[4:5], v[80:81], v[88:89] op_sel_hi:[1,0,1]
	v_pk_fma_f32 v[26:27], v[2:3], v[0:1], v[6:7] op_sel_hi:[1,0,1]
	v_pk_fma_f32 v[24:25], v[4:5], v[0:1], v[8:9] op_sel_hi:[1,0,1]
	v_and_b32_e32 v2, 64, v226
	v_xor_b32_e32 v0, 8, v226
	v_add_u32_e32 v3, 64, v2
	v_cmp_lt_i32_e64 s[42:43], v0, v3
	v_xor_b32_e32 v2, 16, v226
	v_xor_b32_e32 v6, 32, v226
	v_cndmask_b32_e64 v0, v226, v0, s[42:43]
	v_lshlrev_b32_e32 v0, 2, v0
	v_cmp_lt_i32_e64 s[42:43], v2, v3
	s_nop 1
	v_cndmask_b32_e64 v2, v226, v2, s[42:43]
	v_lshlrev_b32_e32 v2, 2, v2
	v_cmp_lt_i32_e64 s[42:43], v6, v3
	s_nop 1
	v_cndmask_b32_e64 v3, v226, v6, s[42:43]
	v_lshlrev_b32_e32 v3, 2, v3
	ds_bpermute_b32 v78, v0, v76
	ds_bpermute_b32 v79, v0, v77
	ds_bpermute_b32 v80, v0, v72
	ds_bpermute_b32 v81, v0, v73
	ds_bpermute_b32 v82, v0, v68
	ds_bpermute_b32 v83, v0, v69
	ds_bpermute_b32 v84, v0, v66
	ds_bpermute_b32 v85, v0, v67
	ds_bpermute_b32 v86, v0, v58
	ds_bpermute_b32 v87, v0, v59
	ds_bpermute_b32 v88, v0, v44
	ds_bpermute_b32 v89, v0, v45
	s_waitcnt lgkmcnt(0)
	v_add_f32_e32 v76, v76, v78
	v_add_f32_e32 v77, v77, v79
	v_add_f32_e32 v72, v72, v80
	v_add_f32_e32 v73, v73, v81
	v_add_f32_e32 v68, v68, v82
	v_add_f32_e32 v69, v69, v83
	v_add_f32_e32 v66, v66, v84
	v_add_f32_e32 v67, v67, v85
	v_add_f32_e32 v58, v58, v86
	v_add_f32_e32 v59, v59, v87
	v_add_f32_e32 v44, v44, v88
	v_add_f32_e32 v45, v45, v89
	ds_bpermute_b32 v78, v2, v76
	ds_bpermute_b32 v79, v2, v77
	ds_bpermute_b32 v80, v2, v72
	ds_bpermute_b32 v81, v2, v73
	ds_bpermute_b32 v82, v2, v68
	ds_bpermute_b32 v83, v2, v69
	ds_bpermute_b32 v84, v2, v66
	ds_bpermute_b32 v85, v2, v67
	ds_bpermute_b32 v86, v2, v58
	ds_bpermute_b32 v87, v2, v59
	ds_bpermute_b32 v88, v2, v44
	ds_bpermute_b32 v89, v2, v45
	s_waitcnt lgkmcnt(0)
	v_add_f32_e32 v76, v76, v78
	v_add_f32_e32 v77, v77, v79
	v_add_f32_e32 v72, v72, v80
	v_add_f32_e32 v73, v73, v81
	v_add_f32_e32 v68, v68, v82
	v_add_f32_e32 v69, v69, v83
	v_add_f32_e32 v66, v66, v84
	v_add_f32_e32 v67, v67, v85
	v_add_f32_e32 v58, v58, v86
	v_add_f32_e32 v59, v59, v87
	v_add_f32_e32 v44, v44, v88
	v_add_f32_e32 v45, v45, v89
	ds_bpermute_b32 v78, v3, v76
	ds_bpermute_b32 v79, v3, v77
	ds_bpermute_b32 v80, v3, v72
	ds_bpermute_b32 v81, v3, v73
	ds_bpermute_b32 v82, v3, v68
	ds_bpermute_b32 v83, v3, v69
	ds_bpermute_b32 v84, v3, v66
	ds_bpermute_b32 v85, v3, v67
	ds_bpermute_b32 v86, v3, v58
	ds_bpermute_b32 v87, v3, v59
	ds_bpermute_b32 v88, v3, v44
	ds_bpermute_b32 v89, v3, v45
	s_waitcnt lgkmcnt(0)
	v_add_f32_e32 v76, v76, v78
	v_add_f32_e32 v77, v77, v79
	v_add_f32_e32 v72, v72, v80
	v_add_f32_e32 v73, v73, v81
	v_add_f32_e32 v68, v68, v82
	v_add_f32_e32 v69, v69, v83
	v_add_f32_e32 v66, v66, v84
	v_add_f32_e32 v67, v67, v85
	v_add_f32_e32 v58, v58, v86
	v_add_f32_e32 v59, v59, v87
	v_add_f32_e32 v44, v44, v88
	v_add_f32_e32 v45, v45, v89
	s_and_saveexec_b64 s[4:5], vcc
	ds_write_b32 v53, v76
	ds_write_b32 v53, v77 offset:4
	ds_write_b32 v53, v72 offset:8
	ds_write_b32 v53, v73 offset:12
	ds_write_b32 v53, v68 offset:128
	ds_write_b32 v53, v69 offset:132
	ds_write_b32 v53, v66 offset:136
	ds_write_b32 v53, v67 offset:140
	ds_write_b32 v53, v58 offset:256
	ds_write_b32 v53, v59 offset:260
	ds_write_b32 v53, v44 offset:264
	ds_write_b32 v53, v45 offset:268
	s_or_b64 exec, exec, s[4:5]
	ds_bpermute_b32 v78, v0, v56
	ds_bpermute_b32 v79, v0, v57
	ds_bpermute_b32 v80, v0, v54
	ds_bpermute_b32 v81, v0, v55
	ds_bpermute_b32 v82, v0, v42
	ds_bpermute_b32 v83, v0, v43
	ds_bpermute_b32 v84, v0, v40
	ds_bpermute_b32 v85, v0, v41
	ds_bpermute_b32 v86, v0, v38
	ds_bpermute_b32 v87, v0, v39
	ds_bpermute_b32 v88, v0, v28
	ds_bpermute_b32 v89, v0, v29
	s_waitcnt lgkmcnt(0)
	v_add_f32_e32 v56, v56, v78
	v_add_f32_e32 v57, v57, v79
	v_add_f32_e32 v54, v54, v80
	v_add_f32_e32 v55, v55, v81
	v_add_f32_e32 v42, v42, v82
	v_add_f32_e32 v43, v43, v83
	v_add_f32_e32 v40, v40, v84
	v_add_f32_e32 v41, v41, v85
	v_add_f32_e32 v38, v38, v86
	v_add_f32_e32 v39, v39, v87
	v_add_f32_e32 v28, v28, v88
	v_add_f32_e32 v29, v29, v89
	ds_bpermute_b32 v78, v2, v56
	ds_bpermute_b32 v79, v2, v57
	ds_bpermute_b32 v80, v2, v54
	ds_bpermute_b32 v81, v2, v55
	ds_bpermute_b32 v82, v2, v42
	ds_bpermute_b32 v83, v2, v43
	ds_bpermute_b32 v84, v2, v40
	ds_bpermute_b32 v85, v2, v41
	ds_bpermute_b32 v86, v2, v38
	ds_bpermute_b32 v87, v2, v39
	ds_bpermute_b32 v88, v2, v28
	ds_bpermute_b32 v89, v2, v29
	s_waitcnt lgkmcnt(0)
	v_add_f32_e32 v56, v56, v78
	v_add_f32_e32 v57, v57, v79
	v_add_f32_e32 v54, v54, v80
	v_add_f32_e32 v55, v55, v81
	v_add_f32_e32 v42, v42, v82
	v_add_f32_e32 v43, v43, v83
	v_add_f32_e32 v40, v40, v84
	v_add_f32_e32 v41, v41, v85
	v_add_f32_e32 v38, v38, v86
	v_add_f32_e32 v39, v39, v87
	v_add_f32_e32 v28, v28, v88
	v_add_f32_e32 v29, v29, v89
	ds_bpermute_b32 v78, v3, v56
	ds_bpermute_b32 v79, v3, v57
	ds_bpermute_b32 v80, v3, v54
	ds_bpermute_b32 v81, v3, v55
	ds_bpermute_b32 v82, v3, v42
	ds_bpermute_b32 v83, v3, v43
	ds_bpermute_b32 v84, v3, v40
	ds_bpermute_b32 v85, v3, v41
	ds_bpermute_b32 v86, v3, v38
	ds_bpermute_b32 v87, v3, v39
	ds_bpermute_b32 v88, v3, v28
	ds_bpermute_b32 v89, v3, v29
	s_waitcnt lgkmcnt(0)
	v_add_f32_e32 v56, v56, v78
	v_add_f32_e32 v57, v57, v79
	v_add_f32_e32 v54, v54, v80
	v_add_f32_e32 v55, v55, v81
	v_add_f32_e32 v42, v42, v82
	v_add_f32_e32 v43, v43, v83
	v_add_f32_e32 v40, v40, v84
	v_add_f32_e32 v41, v41, v85
	v_add_f32_e32 v38, v38, v86
	v_add_f32_e32 v39, v39, v87
	v_add_f32_e32 v28, v28, v88
	v_add_f32_e32 v29, v29, v89
	s_and_saveexec_b64 s[4:5], vcc
	ds_write_b32 v53, v56 offset:384
	ds_write_b32 v53, v57 offset:388
	ds_write_b32 v53, v54 offset:392
	ds_write_b32 v53, v55 offset:396
	ds_write_b32 v53, v42 offset:512
	ds_write_b32 v53, v43 offset:516
	ds_write_b32 v53, v40 offset:520
	ds_write_b32 v53, v41 offset:524
	ds_write_b32 v53, v38 offset:640
	ds_write_b32 v53, v39 offset:644
	ds_write_b32 v53, v28 offset:648
	ds_write_b32 v53, v29 offset:652
	s_or_b64 exec, exec, s[4:5]
	ds_bpermute_b32 v78, v0, v36
	ds_bpermute_b32 v79, v0, v37
	ds_bpermute_b32 v80, v0, v30
	ds_bpermute_b32 v81, v0, v31
	ds_bpermute_b32 v82, v0, v34
	ds_bpermute_b32 v83, v0, v35
	ds_bpermute_b32 v84, v0, v32
	ds_bpermute_b32 v85, v0, v33
	ds_bpermute_b32 v86, v0, v26
	ds_bpermute_b32 v87, v0, v27
	ds_bpermute_b32 v88, v0, v24
	ds_bpermute_b32 v89, v0, v25
	s_waitcnt lgkmcnt(0)
	v_add_f32_e32 v36, v36, v78
	v_add_f32_e32 v37, v37, v79
	v_add_f32_e32 v30, v30, v80
	v_add_f32_e32 v31, v31, v81
	v_add_f32_e32 v34, v34, v82
	v_add_f32_e32 v35, v35, v83
	v_add_f32_e32 v32, v32, v84
	v_add_f32_e32 v33, v33, v85
	v_add_f32_e32 v26, v26, v86
	v_add_f32_e32 v27, v27, v87
	v_add_f32_e32 v24, v24, v88
	v_add_f32_e32 v25, v25, v89
	ds_bpermute_b32 v78, v2, v36
	ds_bpermute_b32 v79, v2, v37
	ds_bpermute_b32 v80, v2, v30
	ds_bpermute_b32 v81, v2, v31
	ds_bpermute_b32 v82, v2, v34
	ds_bpermute_b32 v83, v2, v35
	ds_bpermute_b32 v84, v2, v32
	ds_bpermute_b32 v85, v2, v33
	ds_bpermute_b32 v86, v2, v26
	ds_bpermute_b32 v87, v2, v27
	ds_bpermute_b32 v88, v2, v24
	ds_bpermute_b32 v89, v2, v25
	s_waitcnt lgkmcnt(0)
	v_add_f32_e32 v36, v36, v78
	v_add_f32_e32 v37, v37, v79
	v_add_f32_e32 v30, v30, v80
	v_add_f32_e32 v31, v31, v81
	v_add_f32_e32 v34, v34, v82
	v_add_f32_e32 v35, v35, v83
	v_add_f32_e32 v32, v32, v84
	v_add_f32_e32 v33, v33, v85
	v_add_f32_e32 v26, v26, v86
	v_add_f32_e32 v27, v27, v87
	v_add_f32_e32 v24, v24, v88
	v_add_f32_e32 v25, v25, v89
	ds_bpermute_b32 v78, v3, v36
	ds_bpermute_b32 v79, v3, v37
	ds_bpermute_b32 v80, v3, v30
	ds_bpermute_b32 v81, v3, v31
	ds_bpermute_b32 v82, v3, v34
	ds_bpermute_b32 v83, v3, v35
	ds_bpermute_b32 v84, v3, v32
	ds_bpermute_b32 v85, v3, v33
	ds_bpermute_b32 v86, v3, v26
	ds_bpermute_b32 v87, v3, v27
	ds_bpermute_b32 v88, v3, v24
	ds_bpermute_b32 v89, v3, v25
	s_waitcnt lgkmcnt(0)
	v_add_f32_e32 v36, v36, v78
	v_add_f32_e32 v37, v37, v79
	v_add_f32_e32 v30, v30, v80
	v_add_f32_e32 v31, v31, v81
	v_add_f32_e32 v34, v34, v82
	v_add_f32_e32 v35, v35, v83
	v_add_f32_e32 v32, v32, v84
	v_add_f32_e32 v33, v33, v85
	v_add_f32_e32 v26, v26, v86
	v_add_f32_e32 v27, v27, v87
	v_add_f32_e32 v24, v24, v88
	v_add_f32_e32 v25, v25, v89
	s_and_saveexec_b64 s[4:5], vcc
	ds_write_b32 v53, v36 offset:768
	ds_write_b32 v53, v37 offset:772
	ds_write_b32 v53, v30 offset:776
	ds_write_b32 v53, v31 offset:780
	ds_write_b32 v53, v34 offset:896
	ds_write_b32 v53, v35 offset:900
	ds_write_b32 v53, v32 offset:904
	ds_write_b32 v53, v33 offset:908
	ds_write_b32 v53, v26 offset:1024
	ds_write_b32 v53, v27 offset:1028
	ds_write_b32 v53, v24 offset:1032
	ds_write_b32 v53, v25 offset:1036
	s_or_b64 exec, exec, s[4:5]
